# ret_out: state-fragment loads and unit-start q/k/rope/V loads batched under counted vmcnt (was ~19 serialized round trips per unit)
# baseline (speedup 1.0000x reference)
.LBB0_490:
	s_or_b64 exec, exec, s[0:1]
	v_lshlrev_b32_e32 v70, 7, v6
	v_lshlrev_b32_e32 v2, 3, v5
	v_ashrrev_i32_e32 v71, 31, v70
	v_and_b32_e32 v7, 56, v2
	v_bfe_u32 v13, v5, 3, 5
	v_lshlrev_b64 v[72:73], 1, v[70:71]
	v_lshlrev_b32_e32 v0, 3, v7
	v_mov_b32_e32 v1, v65
	v_or_b32_e32 v8, v3, v13
	v_lshl_add_u64 v[0:1], s[40:41], 0, v[0:1]
	v_lshlrev_b32_e32 v8, 9, v8
	v_mov_b32_e32 v9, v65
	v_lshl_add_u64 v[18:19], s[38:39], 0, v[72:73]
	v_lshlrev_b32_e32 v64, 1, v7
	v_lshl_add_u64 v[38:39], v[0:1], 0, v[8:9]
	v_lshl_add_u64 v[42:43], v[18:19], 0, v[64:65]
	v_add_u32_e32 v7, v68, v13
	flat_load_dwordx4 v[8:11], v[38:39]
	flat_load_dwordx4 v[14:17], v[38:39] offset:16
	flat_load_dwordx4 v[18:21], v[38:39] offset:32
	v_mad_i64_i32 v[34:35], s[0:1], v7, s57, v[42:43]
	flat_load_dwordx4 v[22:25], v[34:35]
	flat_load_dwordx4 v[26:29], v[34:35] offset:128
	flat_load_dwordx4 v[30:33], v[34:35] offset:1536
	s_nop 0
	flat_load_dwordx4 v[34:37], v[34:35] offset:1664
	s_nop 0
	flat_load_dwordx4 v[38:41], v[38:39] offset:48
	v_or_b32_sdwa v140, v5, s61 dst_sel:DWORD dst_unused:UNUSED_PAD src0_sel:BYTE_0 src1_sel:DWORD
	v_lshrrev_b32_e32 v141, 3, v140
	v_add_u32_e32 v142, v68, v141
	v_mad_i64_i32 v[134:135], s[0:1], v142, s57, v[42:43]
	v_or_b32_e32 v143, v3, v141
	v_lshlrev_b32_e32 v136, 9, v143
	v_mov_b32_e32 v137, v65
	v_lshl_add_u64 v[136:137], v[0:1], 0, v[136:137]
	global_load_dwordx4 v[160:163], v[134:135], off
	global_load_dwordx4 v[164:167], v[134:135], off offset:128
	global_load_dwordx4 v[168:171], v[134:135], off offset:1536
	global_load_dwordx4 v[172:175], v[134:135], off offset:1664
	global_load_dwordx4 v[176:179], v[136:137], off
	global_load_dwordx4 v[180:183], v[136:137], off offset:16
	global_load_dwordx4 v[184:187], v[136:137], off offset:32
	global_load_dwordx4 v[188:191], v[136:137], off offset:48
	v_bfe_u32 v140, v5, 4, 4
	v_add_u32_e32 v140, v68, v140
	v_mad_i64_i32 v[138:139], s[0:1], v140, s57, v[66:67]
	v_lshl_add_u64 v[138:139], v[138:139], 0, v[72:73]
	v_lshlrev_b32_e32 v140, 3, v5
	v_and_b32_e32 v140, 0x78, v140
	v_lshlrev_b32_e32 v140, 1, v140
	v_mov_b32_e32 v141, v65
	v_lshl_add_u64 v[138:139], v[138:139], 0, v[140:141]
	v_mov_b32_e32 v140, 0x1a000
	global_load_dwordx4 v[192:195], v[138:139], off offset:3072
	v_lshl_add_u64 v[138:139], v[138:139], 0, v[140:141]
	global_load_dwordx4 v[196:199], v[138:139], off offset:3072
	v_lshl_add_u64 v[138:139], v[138:139], 0, v[140:141]
	global_load_dwordx4 v[200:203], v[138:139], off offset:3072
	v_lshl_add_u64 v[138:139], v[138:139], 0, v[140:141]
	global_load_dwordx4 v[204:207], v[138:139], off offset:3072
	v_mul_u32_u24_e32 v7, 0x88, v13
	v_mad_i32_i24 v4, v4, s52, 0
	v_lshlrev_b32_e32 v7, 1, v7
	v_add3_u32 v7, v4, v7, v64
	s_add_i32 s2, s2, s84
	s_waitcnt vmcnt(12) lgkmcnt(0)
	v_mov_b32_e32 v44, v8
	v_mov_b32_e32 v45, v10
	v_mov_b32_e32 v10, v9
	v_mov_b32_e32 v8, v14
	v_mov_b32_e32 v9, v16
	v_mov_b32_e32 v16, v15
	v_mov_b32_e32 v14, v18
	v_mov_b32_e32 v15, v20
	v_mov_b32_e32 v20, v19
	v_lshlrev_b32_e32 v18, 16, v22
	v_and_b32_e32 v19, 0xffff0000, v22
	v_lshlrev_b32_e32 v22, 16, v23
	v_and_b32_e32 v23, 0xffff0000, v23
	v_lshlrev_b32_e32 v48, 16, v26
	v_and_b32_e32 v49, 0xffff0000, v26
	v_lshlrev_b32_e32 v26, 16, v27
	v_and_b32_e32 v27, 0xffff0000, v27
	v_lshlrev_b32_e32 v52, 16, v30
	v_and_b32_e32 v53, 0xffff0000, v30
	v_lshlrev_b32_e32 v30, 16, v31
	v_and_b32_e32 v31, 0xffff0000, v31
	v_lshlrev_b32_e32 v56, 16, v34
	v_and_b32_e32 v57, 0xffff0000, v34
	v_lshlrev_b32_e32 v34, 16, v35
	v_and_b32_e32 v35, 0xffff0000, v35
	v_pk_mul_f32 v[76:77], v[16:17], v[26:27]
	v_pk_mul_f32 v[84:85], v[16:17], v[22:23]
	v_pk_mul_f32 v[86:87], v[16:17], v[34:35]
	v_pk_mul_f32 v[16:17], v[16:17], v[30:31]
	v_lshlrev_b32_e32 v46, 16, v24
	v_and_b32_e32 v47, 0xffff0000, v24
	v_lshlrev_b32_e32 v50, 16, v28
	v_and_b32_e32 v51, 0xffff0000, v28
	v_pk_mul_f32 v[60:61], v[10:11], v[48:49]
	v_pk_mul_f32 v[62:63], v[10:11], v[18:19]
	v_pk_mul_f32 v[74:75], v[10:11], v[56:57]
	v_pk_mul_f32 v[10:11], v[10:11], v[52:53]
	v_pk_fma_f32 v[22:23], v[8:9], v[22:23], v[76:77] neg_lo:[0,0,1] neg_hi:[0,0,1]
	v_pk_fma_f32 v[26:27], v[8:9], v[26:27], v[84:85]
	v_pk_fma_f32 v[30:31], v[8:9], v[30:31], v[86:87] neg_lo:[0,0,1] neg_hi:[0,0,1]
	v_pk_fma_f32 v[8:9], v[8:9], v[34:35], v[16:17]
	v_lshlrev_b32_e32 v58, 16, v36
	v_and_b32_e32 v59, 0xffff0000, v36
	v_pk_mul_f32 v[88:89], v[20:21], v[50:51]
	v_pk_fma_f32 v[18:19], v[44:45], v[18:19], v[60:61] neg_lo:[0,0,1] neg_hi:[0,0,1]
	v_pk_fma_f32 v[48:49], v[44:45], v[48:49], v[62:63]
	v_pk_fma_f32 v[52:53], v[44:45], v[52:53], v[74:75] neg_lo:[0,0,1] neg_hi:[0,0,1]
	v_pk_fma_f32 v[10:11], v[44:45], v[56:57], v[10:11]
	v_pk_mul_f32 v[44:45], v[8:9], s[44:45] op_sel_hi:[1,0]
	v_pk_mul_f32 v[8:9], v[20:21], v[46:47]
	v_lshlrev_b32_e32 v54, 16, v32
	v_and_b32_e32 v55, 0xffff0000, v32
	v_pk_mul_f32 v[34:35], v[10:11], s[44:45] op_sel_hi:[1,0]
	v_pk_fma_f32 v[10:11], v[14:15], v[46:47], v[88:89] neg_lo:[0,0,1] neg_hi:[0,0,1]
	v_pk_fma_f32 v[46:47], v[14:15], v[50:51], v[8:9]
	v_pk_mul_f32 v[8:9], v[20:21], v[58:59]
	v_lshlrev_b32_e32 v28, 16, v29
	v_pk_fma_f32 v[8:9], v[14:15], v[54:55], v[8:9] neg_lo:[0,0,1] neg_hi:[0,0,1]
	v_and_b32_e32 v29, 0xffff0000, v29
	v_pk_mul_f32 v[50:51], v[8:9], s[44:45] op_sel_hi:[1,0]
	v_pk_mul_f32 v[8:9], v[20:21], v[54:55]
	v_lshlrev_b32_e32 v24, 16, v25
	v_pk_fma_f32 v[8:9], v[14:15], v[58:59], v[8:9]
	v_and_b32_e32 v25, 0xffff0000, v25
	v_pk_mul_f32 v[14:15], v[8:9], s[44:45] op_sel_hi:[1,0]
	v_mov_b32_e32 v9, v40
	v_mov_b32_e32 v40, v39
	v_mov_b32_e32 v8, v38
	v_pk_mul_f32 v[20:21], v[40:41], v[28:29]
	v_lshlrev_b32_e32 v36, 16, v37
	v_and_b32_e32 v37, 0xffff0000, v37
	v_pk_fma_f32 v[20:21], v[8:9], v[24:25], v[20:21] neg_lo:[0,0,1] neg_hi:[0,0,1]
	v_pk_mul_f32 v[24:25], v[40:41], v[24:25]
	v_lshlrev_b32_e32 v32, 16, v33
	v_and_b32_e32 v33, 0xffff0000, v33
	v_pk_fma_f32 v[24:25], v[8:9], v[28:29], v[24:25]
	v_pk_mul_f32 v[28:29], v[40:41], v[36:37]
	v_cvt_pk_bf16_f32 v10, v10, v11
	v_pk_fma_f32 v[28:29], v[8:9], v[32:33], v[28:29] neg_lo:[0,0,1] neg_hi:[0,0,1]
	v_pk_mul_f32 v[32:33], v[40:41], v[32:33]
	v_cvt_pk_bf16_f32 v11, v20, v21
	v_pk_fma_f32 v[8:9], v[8:9], v[36:37], v[32:33]
	v_pk_mul_f32 v[16:17], v[52:53], s[44:45] op_sel_hi:[1,0]
	v_pk_mul_f32 v[32:33], v[8:9], s[44:45] op_sel_hi:[1,0]
	v_cvt_pk_bf16_f32 v8, v18, v19
	v_cvt_pk_bf16_f32 v9, v22, v23
	v_pk_mul_f32 v[30:31], v[30:31], s[44:45] op_sel_hi:[1,0]
	v_pk_mul_f32 v[28:29], v[28:29], s[44:45] op_sel_hi:[1,0]
	ds_write_b128 v7, v[8:11]
	v_cvt_pk_bf16_f32 v8, v48, v49
	v_cvt_pk_bf16_f32 v9, v26, v27
	v_cvt_pk_bf16_f32 v10, v46, v47
	v_cvt_pk_bf16_f32 v11, v24, v25
	ds_write_b128 v7, v[8:11] offset:128
	v_cvt_pk_bf16_f32 v8, v16, v17
	v_cvt_pk_bf16_f32 v9, v30, v31
	v_cvt_pk_bf16_f32 v10, v50, v51
	v_cvt_pk_bf16_f32 v11, v28, v29
	ds_write_b128 v7, v[8:11] offset:17408
	v_cvt_pk_bf16_f32 v8, v34, v35
	v_cvt_pk_bf16_f32 v9, v44, v45
	v_cvt_pk_bf16_f32 v10, v14, v15
	v_cvt_pk_bf16_f32 v11, v32, v33
	ds_write_b128 v7, v[8:11] offset:17536
	v_or_b32_sdwa v7, v5, s61 dst_sel:DWORD dst_unused:UNUSED_PAD src0_sel:BYTE_0 src1_sel:DWORD
	v_lshrrev_b32_e32 v13, 3, v7
	v_add_u32_e32 v8, v68, v13
	v_or_b32_e32 v3, v3, v13
	v_mad_i64_i32 v[22:23], s[0:1], v8, s57, v[42:43]
	v_lshlrev_b32_e32 v26, 9, v3
	v_mov_b32_e32 v27, v65
	s_nop 0
	v_lshl_add_u64 v[0:1], v[0:1], 0, v[26:27]
	v_mul_u32_u24_e32 v3, 0x88, v13
	v_lshlrev_b32_e32 v3, 1, v3
	v_add3_u32 v3, v4, v3, v64
	v_lshrrev_b32_e32 v7, 4, v7
	s_waitcnt vmcnt(4) lgkmcnt(0)
	v_mov_b64_e32 v[8:9], v[160:161]
	v_mov_b64_e32 v[10:11], v[162:163]
	v_mov_b64_e32 v[14:15], v[164:165]
	v_mov_b64_e32 v[16:17], v[166:167]
	v_mov_b64_e32 v[18:19], v[168:169]
	v_mov_b64_e32 v[20:21], v[170:171]
	v_mov_b64_e32 v[22:23], v[172:173]
	v_mov_b64_e32 v[24:25], v[174:175]
	v_mov_b64_e32 v[26:27], v[176:177]
	v_mov_b64_e32 v[28:29], v[178:179]
	v_mov_b64_e32 v[30:31], v[180:181]
	v_mov_b64_e32 v[32:33], v[182:183]
	v_mov_b64_e32 v[34:35], v[184:185]
	v_mov_b64_e32 v[36:37], v[186:187]
	v_mov_b64_e32 v[38:39], v[188:189]
	v_mov_b64_e32 v[40:41], v[190:191]
	v_lshlrev_b32_e32 v0, 16, v8
	v_lshlrev_b32_e32 v44, 16, v14
	v_and_b32_e32 v45, 0xffff0000, v14
	v_mov_b32_e32 v57, v28
	v_mov_b32_e32 v28, v27
	v_and_b32_e32 v1, 0xffff0000, v8
	v_mov_b32_e32 v56, v26
	v_pk_mul_f32 v[26:27], v[28:29], v[44:45]
	v_lshlrev_b32_e32 v52, 16, v22
	v_and_b32_e32 v53, 0xffff0000, v22
	v_pk_fma_f32 v[26:27], v[56:57], v[0:1], v[26:27] neg_lo:[0,0,1] neg_hi:[0,0,1]
	v_pk_mul_f32 v[0:1], v[28:29], v[0:1]
	v_lshlrev_b32_e32 v48, 16, v18
	v_and_b32_e32 v49, 0xffff0000, v18
	v_pk_fma_f32 v[0:1], v[56:57], v[44:45], v[0:1]
	v_pk_mul_f32 v[44:45], v[28:29], v[52:53]
	v_lshlrev_b32_e32 v14, 16, v15
	v_and_b32_e32 v15, 0xffff0000, v15
	v_pk_fma_f32 v[44:45], v[56:57], v[48:49], v[44:45] neg_lo:[0,0,1] neg_hi:[0,0,1]
	v_pk_mul_f32 v[28:29], v[28:29], v[48:49]
	v_mov_b32_e32 v49, v32
	v_mov_b32_e32 v32, v31
	v_lshlrev_b32_e32 v8, 16, v9
	v_and_b32_e32 v9, 0xffff0000, v9
	v_mov_b32_e32 v48, v30
	v_pk_mul_f32 v[30:31], v[32:33], v[14:15]
	v_lshlrev_b32_e32 v22, 16, v23
	v_and_b32_e32 v23, 0xffff0000, v23
	v_pk_fma_f32 v[30:31], v[48:49], v[8:9], v[30:31] neg_lo:[0,0,1] neg_hi:[0,0,1]
	v_pk_mul_f32 v[8:9], v[32:33], v[8:9]
	v_lshlrev_b32_e32 v18, 16, v19
	v_and_b32_e32 v19, 0xffff0000, v19
	v_pk_fma_f32 v[14:15], v[48:49], v[14:15], v[8:9]
	v_pk_mul_f32 v[8:9], v[32:33], v[22:23]
	v_pk_fma_f32 v[28:29], v[56:57], v[52:53], v[28:29]
	v_pk_fma_f32 v[8:9], v[48:49], v[18:19], v[8:9] neg_lo:[0,0,1] neg_hi:[0,0,1]
	v_lshlrev_b32_e32 v42, 16, v10
	v_pk_mul_f32 v[52:53], v[8:9], s[44:45] op_sel_hi:[1,0]
	v_pk_mul_f32 v[8:9], v[32:33], v[18:19]
	v_and_b32_e32 v43, 0xffff0000, v10
	v_pk_fma_f32 v[8:9], v[48:49], v[22:23], v[8:9]
	v_lshlrev_b32_e32 v46, 16, v16
	v_and_b32_e32 v47, 0xffff0000, v16
	v_lshlrev_b32_e32 v50, 16, v20
	v_and_b32_e32 v51, 0xffff0000, v20
	v_lshlrev_b32_e32 v54, 16, v24
	v_and_b32_e32 v55, 0xffff0000, v24
	v_pk_mul_f32 v[18:19], v[8:9], s[44:45] op_sel_hi:[1,0]
	v_mov_b32_e32 v9, v36
	v_mov_b32_e32 v36, v35
	v_mov_b32_e32 v8, v34
	v_pk_mul_f32 v[22:23], v[36:37], v[46:47]
	v_pk_mul_f32 v[32:33], v[36:37], v[42:43]
	v_pk_mul_f32 v[34:35], v[36:37], v[54:55]
	v_pk_mul_f32 v[36:37], v[36:37], v[50:51]
	v_pk_fma_f32 v[22:23], v[8:9], v[42:43], v[22:23] neg_lo:[0,0,1] neg_hi:[0,0,1]
	v_pk_fma_f32 v[32:33], v[8:9], v[46:47], v[32:33]
	v_pk_fma_f32 v[34:35], v[8:9], v[50:51], v[34:35] neg_lo:[0,0,1] neg_hi:[0,0,1]
	v_pk_fma_f32 v[8:9], v[8:9], v[54:55], v[36:37]
	v_lshlrev_b32_e32 v16, 16, v17
	v_and_b32_e32 v17, 0xffff0000, v17
	v_pk_mul_f32 v[36:37], v[8:9], s[44:45] op_sel_hi:[1,0]
	v_mov_b32_e32 v9, v40
	v_mov_b32_e32 v40, v39
	v_lshlrev_b32_e32 v10, 16, v11
	v_and_b32_e32 v11, 0xffff0000, v11
	v_mov_b32_e32 v8, v38
	v_pk_mul_f32 v[38:39], v[40:41], v[16:17]
	v_lshlrev_b32_e32 v24, 16, v25
	v_and_b32_e32 v25, 0xffff0000, v25
	v_pk_fma_f32 v[38:39], v[8:9], v[10:11], v[38:39] neg_lo:[0,0,1] neg_hi:[0,0,1]
	v_pk_mul_f32 v[10:11], v[40:41], v[10:11]
	v_lshlrev_b32_e32 v20, 16, v21
	v_and_b32_e32 v21, 0xffff0000, v21
	v_pk_fma_f32 v[16:17], v[8:9], v[16:17], v[10:11]
	v_pk_mul_f32 v[10:11], v[40:41], v[24:25]
	v_pk_mul_f32 v[44:45], v[44:45], s[44:45] op_sel_hi:[1,0]
	v_pk_fma_f32 v[10:11], v[8:9], v[20:21], v[10:11] neg_lo:[0,0,1] neg_hi:[0,0,1]
	v_pk_mul_f32 v[34:35], v[34:35], s[44:45] op_sel_hi:[1,0]
	v_pk_mul_f32 v[42:43], v[10:11], s[44:45] op_sel_hi:[1,0]
	v_pk_mul_f32 v[10:11], v[40:41], v[20:21]
	v_pk_mul_f32 v[28:29], v[28:29], s[44:45] op_sel_hi:[1,0]
	v_pk_fma_f32 v[8:9], v[8:9], v[24:25], v[10:11]
	v_cvt_pk_bf16_f32 v10, v22, v23
	v_pk_mul_f32 v[20:21], v[8:9], s[44:45] op_sel_hi:[1,0]
	v_cvt_pk_bf16_f32 v8, v26, v27
	v_cvt_pk_bf16_f32 v9, v30, v31
	v_cvt_pk_bf16_f32 v11, v38, v39
	ds_write_b128 v3, v[8:11]
	v_cvt_pk_bf16_f32 v8, v0, v1
	v_cvt_pk_bf16_f32 v9, v14, v15
	v_cvt_pk_bf16_f32 v10, v32, v33
	v_cvt_pk_bf16_f32 v11, v16, v17
	ds_write_b128 v3, v[8:11] offset:128
	v_cvt_pk_bf16_f32 v8, v44, v45
	v_cvt_pk_bf16_f32 v9, v52, v53
	v_cvt_pk_bf16_f32 v10, v34, v35
	v_cvt_pk_bf16_f32 v11, v42, v43
	ds_write_b128 v3, v[8:11] offset:17408
	v_cvt_pk_bf16_f32 v8, v28, v29
	v_cvt_pk_bf16_f32 v9, v18, v19
	v_cvt_pk_bf16_f32 v10, v36, v37
	v_cvt_pk_bf16_f32 v11, v20, v21
	ds_write_b128 v3, v[8:11] offset:17536
	v_bfe_u32 v9, v5, 4, 4
	v_add_u32_e32 v10, v68, v9
	v_and_b32_e32 v8, 0x78, v2
	v_mad_i64_i32 v[0:1], s[0:1], v10, s57, v[66:67]
	v_lshl_add_u64 v[0:1], v[0:1], 0, v[72:73]
	v_lshlrev_b32_e32 v64, 1, v8
	v_lshl_add_u64 v[0:1], v[0:1], 0, v[64:65]
	v_mul_u32_u24_e32 v8, 0x48, v8
	v_lshlrev_b32_e32 v11, 1, v8
	v_lshlrev_b32_e32 v9, 1, v9
	v_add_u32_e32 v14, v4, v11
	v_add3_u32 v13, v4, v9, v11
	v_add_u32_e32 v15, v14, v9
	v_add_u32_e32 v8, 32, v10
	v_mad_i64_i32 v[8:9], s[0:1], v8, s57, v[66:67]
	v_lshl_add_u64 v[8:9], v[8:9], 0, v[72:73]
	v_lshl_add_u64 v[8:9], v[8:9], 0, v[64:65]
	v_and_b32_e32 v20, 15, v5
	v_bfe_u32 v21, v5, 4, 2
	v_lshrrev_b32_e32 v5, 2, v5
	v_and_or_b32 v76, v5, 48, v20
	v_lshlrev_b32_e32 v5, 2, v21
	v_lshlrev_b32_e32 v74, 4, v21
	v_sub_u32_e32 v69, v76, v5
	v_add_u32_e32 v16, -2, v69
	v_cvt_f32_i32_e32 v16, v16
	v_add_u32_e32 v17, -3, v69
	v_subrev_u32_e32 v22, 17, v69
	v_subrev_u32_e32 v23, 18, v69
	v_subrev_u32_e32 v24, 19, v69
	v_subrev_u32_e32 v25, 33, v69
	v_cvt_f32_i32_e32 v17, v17
	v_cvt_f32_i32_e32 v22, v22
	v_cvt_f32_i32_e32 v23, v23
	v_cvt_f32_i32_e32 v24, v24
	v_cvt_f32_i32_e32 v25, v25
	v_subrev_u32_e32 v26, 34, v69
	v_subrev_u32_e32 v27, 35, v69
	v_cvt_f32_i32_e32 v26, v26
	v_cvt_f32_i32_e32 v34, v27
	v_subrev_u32_e32 v28, 49, v69
	s_add_i32 s45, s45, s48
	s_cmpk_gt_i32 s2, 0x62f
	s_waitcnt vmcnt(3) lgkmcnt(0)
	v_mov_b64_e32 v[0:1], v[192:193]
	v_mov_b64_e32 v[2:3], v[194:195]
	ds_write_b16 v13, v0 offset:34816
	ds_write_b16_d16_hi v15, v0 offset:34960
	ds_write_b16 v13, v1 offset:35104
	ds_write_b16_d16_hi v15, v1 offset:35248
	ds_write_b16 v13, v2 offset:35392
	ds_write_b16_d16_hi v15, v2 offset:35536
	ds_write_b16 v13, v3 offset:35680
	ds_write_b16_d16_hi v15, v3 offset:35824
	v_add_u32_e32 v0, v68, v7
	v_mad_i64_i32 v[0:1], s[0:1], v0, s57, v[66:67]
	v_lshl_add_u64 v[0:1], v[0:1], 0, v[72:73]
	v_lshl_add_u64 v[0:1], v[0:1], 0, v[64:65]
	v_lshlrev_b32_e32 v7, 1, v7
	v_add3_u32 v11, v4, v7, v11
	v_add_u32_e32 v7, v14, v7
	s_waitcnt vmcnt(2) lgkmcnt(0)
	v_mov_b64_e32 v[0:1], v[196:197]
	v_mov_b64_e32 v[2:3], v[198:199]
	ds_write_b16 v11, v0 offset:34816
	ds_write_b16_d16_hi v7, v0 offset:34960
	ds_write_b16 v11, v1 offset:35104
	ds_write_b16_d16_hi v7, v1 offset:35248
	ds_write_b16 v11, v2 offset:35392
	ds_write_b16_d16_hi v7, v2 offset:35536
	ds_write_b16 v11, v3 offset:35680
	ds_write_b16_d16_hi v7, v3 offset:35824
	v_cvt_f32_i32_e32 v8, v6
	v_add_u32_e32 v6, 48, v10
	v_mad_i64_i32 v[6:7], s[0:1], v6, s57, v[66:67]
	v_lshl_add_u64 v[6:7], v[6:7], 0, v[72:73]
	v_lshl_add_u64 v[6:7], v[6:7], 0, v[64:65]
	s_waitcnt vmcnt(1) lgkmcnt(0)
	v_mov_b64_e32 v[0:1], v[200:201]
	v_mov_b64_e32 v[2:3], v[202:203]
	ds_write_b16 v13, v0 offset:34880
	ds_write_b16_d16_hi v15, v0 offset:35024
	ds_write_b16 v13, v1 offset:35168
	ds_write_b16_d16_hi v15, v1 offset:35312
	ds_write_b16 v13, v2 offset:35456
	ds_write_b16_d16_hi v15, v2 offset:35600
	ds_write_b16 v13, v3 offset:35744
	ds_write_b16_d16_hi v15, v3 offset:35888
	v_sub_f32_e32 v8, 0xc0a00000, v8
	v_cmp_gt_f32_e32 vcc, s53, v8
	v_add_u32_e32 v9, v4, v74
	v_xad_u32 v10, v5, -1, v76
	v_cndmask_b32_e32 v29, 0, v78, vcc
	v_add_f32_e32 v8, v8, v29
	v_exp_f32_e32 v6, v8
	v_cndmask_b32_e32 v7, 0, v79, vcc
	v_mad_u32_u24 v18, v76, s62, v9
	v_mad_u32_u24 v19, v20, s62, v9
	v_ldexp_f32 v6, v6, v7
	v_sub_f32_e32 v6, 1.0, v6
	v_cmp_gt_f32_e32 vcc, s54, v6
	v_cvt_f32_i32_e32 v9, v69
	v_cvt_f32_i32_e32 v10, v10
	v_cndmask_b32_e64 v7, 0, 32, vcc
	v_ldexp_f32 v6, v6, v7
	v_log_f32_e32 v6, v6
	v_cndmask_b32_e32 v7, 0, v80, vcc
	v_or_b32_e32 v14, 32, v5
	s_waitcnt vmcnt(0) lgkmcnt(0)
	v_mov_b64_e32 v[0:1], v[204:205]
	v_mov_b64_e32 v[2:3], v[206:207]
	ds_write_b16 v13, v0 offset:34912
	ds_write_b16_d16_hi v15, v0 offset:35056
	ds_write_b16 v13, v1 offset:35200
	ds_write_b16_d16_hi v15, v1 offset:35344
	ds_write_b16 v13, v2 offset:35488
	ds_write_b16_d16_hi v15, v2 offset:35632
	ds_write_b16 v13, v3 offset:35776
	ds_write_b16_d16_hi v15, v3 offset:35920
	v_mul_f32_e32 v8, 0x3f317217, v6
	v_fma_f32 v8, v6, s55, -v8
	v_fmac_f32_e32 v8, 0x3377d1cf, v6
	v_fmac_f32_e32 v8, 0x3f317217, v6
	v_cmp_lt_f32_e64 vcc, |v6|, s56
	s_waitcnt lgkmcnt(0)
	s_barrier
	v_cndmask_b32_e32 v6, v6, v8, vcc
	v_sub_f32_e32 v6, v6, v7
	ds_read_b128 v[0:3], v19 offset:17408
	v_sub_u32_e32 v14, v76, v14
	v_mul_f32_e32 v83, 0x3fb8aa3b, v6
	v_cvt_f32_i32_e32 v14, v14
	v_mul_f32_e64 v6, |v9|, v83
	v_mul_f32_e64 v7, |v10|, v83
	v_mul_f32_e64 v8, |v16|, v83
	v_cmp_gt_f32_e32 vcc, s53, v6
	v_cmp_gt_f32_e64 s[0:1], s53, v7
	v_cmp_gt_f32_e64 s[4:5], s53, v8
	v_or_b32_e32 v11, 16, v5
	v_or_b32_e32 v5, 48, v5
	v_cndmask_b32_e32 v6, 0, v78, vcc
	v_cndmask_b32_e64 v7, 0, v78, s[0:1]
	v_cndmask_b32_e64 v8, 0, v78, s[4:5]
	v_sub_u32_e32 v11, v76, v11
	v_sub_u32_e32 v5, v76, v5
	v_fma_f32 v42, |v9|, v83, v6
	v_fma_f32 v10, |v10|, v83, v7
	v_fma_f32 v43, |v16|, v83, v8
	ds_read_b128 v[56:59], v18
	ds_read_b128 v[6:9], v19 offset:21760
	v_cvt_f32_i32_e32 v11, v11
	v_cvt_f32_i32_e32 v5, v5
	v_mul_f32_e64 v27, |v17|, v83
	v_mul_f32_e64 v29, |v22|, v83
	v_mul_f32_e64 v30, |v23|, v83
	v_mul_f32_e64 v31, |v24|, v83
	v_mul_f32_e64 v32, |v14|, v83
	v_mul_f32_e64 v33, |v25|, v83
	v_cmp_gt_f32_e64 s[6:7], s53, v27
	v_cmp_gt_f32_e64 s[10:11], s53, v29
	v_cmp_gt_f32_e64 s[12:13], s53, v30
	v_cmp_gt_f32_e64 s[14:15], s53, v31
	v_cmp_gt_f32_e64 s[16:17], s53, v32
	v_cmp_gt_f32_e64 s[18:19], s53, v33
	v_cndmask_b32_e64 v27, 0, v78, s[6:7]
	v_cndmask_b32_e64 v29, 0, v78, s[10:11]
	v_cndmask_b32_e64 v30, 0, v78, s[12:13]
	v_cndmask_b32_e64 v31, 0, v78, s[14:15]
	v_cndmask_b32_e64 v32, 0, v78, s[16:17]
	v_cndmask_b32_e64 v33, 0, v78, s[18:19]
	v_fma_f32 v44, |v17|, v83, v27
	v_fma_f32 v45, |v22|, v83, v29
	v_fma_f32 v48, |v23|, v83, v30
	v_fma_f32 v49, |v24|, v83, v31
	v_fma_f32 v50, |v14|, v83, v32
	v_fma_f32 v13, |v25|, v83, v33
	ds_read_b128 v[60:63], v18 offset:64
	ds_read_b128 v[14:17], v19 offset:17472
	ds_read_b128 v[22:25], v19 offset:26112
	s_waitcnt lgkmcnt(4)
	v_mfma_f32_16x16x32_bf16 v[0:3], v[0:3], v[56:59], 0
	v_cvt_f32_i32_e32 v64, v28
	v_mul_f32_e64 v28, |v11|, v83
	v_mul_f32_e64 v35, |v26|, v83
	v_mul_f32_e64 v36, |v34|, v83
	v_mul_f32_e64 v37, |v5|, v83
	v_cmp_gt_f32_e64 s[8:9], s53, v28
	v_cmp_gt_f32_e64 s[20:21], s53, v35
	v_cmp_gt_f32_e64 s[22:23], s53, v36
	v_cmp_gt_f32_e64 s[24:25], s53, v37
	v_cndmask_b32_e64 v28, 0, v78, s[8:9]
	v_cndmask_b32_e64 v35, 0, v78, s[20:21]
	v_cndmask_b32_e64 v36, 0, v78, s[22:23]
	v_cndmask_b32_e64 v38, 0, v78, s[24:25]
	v_fma_f32 v11, |v11|, v83, v28
	v_fma_f32 v91, |v26|, v83, v35
	ds_read_b128 v[26:29], v19 offset:21824
	ds_read_b128 v[30:33], v19 offset:30464
	v_fma_f32 v93, |v34|, v83, v36
	ds_read_b128 v[34:37], v19 offset:26176
	v_fma_f32 v5, |v5|, v83, v38
	ds_read_b128 v[38:41], v19 offset:30528
	s_waitcnt lgkmcnt(5)
	v_mfma_f32_16x16x32_bf16 v[0:3], v[14:17], v[60:63], v[0:3]
	ds_read_b128 v[14:17], v19 offset:17536
	v_exp_f32_e32 v102, v48
	v_exp_f32_e32 v103, v49
	v_mfma_f32_16x16x32_bf16 v[6:9], v[6:9], v[56:59], 0
	v_exp_f32_e32 v104, v50
	v_exp_f32_e32 v96, v42
	v_exp_f32_e32 v97, v10
	s_waitcnt lgkmcnt(5)
	v_mfma_f32_16x16x32_bf16 v[22:25], v[22:25], v[56:59], 0
	v_exp_f32_e32 v98, v43
	v_exp_f32_e32 v99, v44
	v_exp_f32_e32 v101, v45
	s_waitcnt lgkmcnt(3)
	v_mfma_f32_16x16x32_bf16 v[30:33], v[30:33], v[56:59], 0
	v_mul_f32_e64 v75, |v64|, v83
	v_cndmask_b32_e32 v46, 0, v79, vcc
	v_cndmask_b32_e64 v47, 0, v79, s[0:1]
	v_mfma_f32_16x16x32_bf16 v[6:9], v[26:29], v[60:63], v[6:9]
	ds_read_b128 v[52:55], v18 offset:128
	ds_read_b128 v[26:29], v19 offset:21888
	v_exp_f32_e32 v100, v11
	v_ldexp_f32 v10, v96, v46
	s_waitcnt lgkmcnt(4)
	v_mfma_f32_16x16x32_bf16 v[22:25], v[34:37], v[60:63], v[22:25]
	v_ldexp_f32 v11, v97, v47
	v_cmp_gt_f32_e32 vcc, s53, v75
	v_cndmask_b32_e64 v77, 0, v79, s[4:5]
	s_waitcnt lgkmcnt(3)
	v_mfma_f32_16x16x32_bf16 v[30:33], v[38:41], v[60:63], v[30:33]
	ds_read_b128 v[48:51], v18 offset:192
	ds_read_b128 v[34:37], v19 offset:17600
	ds_read_b128 v[38:41], v19 offset:26240
	v_cndmask_b32_e64 v84, 0, v79, s[6:7]
	v_ldexp_f32 v18, v98, v77
	s_waitcnt lgkmcnt(4)
	v_mfma_f32_16x16x32_bf16 v[0:3], v[14:17], v[52:55], v[0:3]
	ds_read_b128 v[14:17], v19 offset:21952
	ds_read_b128 v[42:45], v19 offset:30592
	v_exp_f32_e32 v13, v13
	v_exp_f32_e32 v91, v91
	s_waitcnt lgkmcnt(3)
	v_mfma_f32_16x16x32_bf16 v[0:3], v[34:37], v[48:51], v[0:3]
	v_exp_f32_e32 v93, v93
	v_cndmask_b32_e64 v90, 0, v79, s[18:19]
	v_cndmask_b32_e64 v89, 0, v79, s[16:17]
	v_mfma_f32_16x16x32_bf16 v[6:9], v[26:29], v[52:55], v[6:9]
	ds_read_b128 v[26:29], v19 offset:26304
	s_nop 2
	v_pk_mul_f32 v[10:11], v[10:11], v[0:1]
	v_cndmask_b32_e32 v0, 0, v78, vcc
	v_fma_f32 v0, |v64|, v83, v0
	v_subrev_u32_e32 v1, 50, v69
	s_waitcnt lgkmcnt(3)
	v_mfma_f32_16x16x32_bf16 v[22:25], v[38:41], v[52:55], v[22:25]
	v_exp_f32_e32 v0, v0
	v_cvt_f32_i32_e32 v1, v1
	ds_read_b128 v[38:41], v19 offset:30656
	v_ldexp_f32 v19, v99, v84
	v_pk_mul_f32 v[18:19], v[18:19], v[2:3]
	v_cndmask_b32_e32 v2, 0, v79, vcc
	s_waitcnt lgkmcnt(3)
	v_mfma_f32_16x16x32_bf16 v[6:9], v[14:17], v[48:51], v[6:9]
	v_lshlrev_b32_e32 v64, 3, v21
	v_cndmask_b32_e64 v92, 0, v79, s[20:21]
	v_cndmask_b32_e64 v94, 0, v79, s[22:23]
	s_waitcnt lgkmcnt(1)
	v_mfma_f32_16x16x32_bf16 v[14:17], v[26:29], v[48:51], v[22:25]
	v_ldexp_f32 v29, v0, v2
	v_mul_f32_e64 v0, |v1|, v83
	v_cmp_gt_f32_e32 vcc, s53, v0
	v_mfma_f32_16x16x32_bf16 v[30:33], v[42:45], v[52:55], v[30:33]
	v_ldexp_f32 v43, v13, v90
	v_cndmask_b32_e32 v0, 0, v78, vcc
	v_fma_f32 v13, |v1|, v83, v0
	v_mul_u32_u24_e32 v0, 0x90, v20
	v_add3_u32 v21, v4, v64, v0
	v_exp_f32_e32 v5, v5
	v_ldexp_f32 v42, v104, v89
	v_ldexp_f32 v26, v91, v92
	v_ldexp_f32 v27, v93, v94
	v_add_u32_e32 v92, 0x9800, v21
	v_pk_mul_f32 v[46:47], v[42:43], v[14:15]
	v_pk_mul_f32 v[90:91], v[26:27], v[16:17]
	ds_read2_b64 v[14:17], v92 offset0:64 offset1:68
	v_exp_f32_e32 v13, v13
	v_cndmask_b32_e64 v95, 0, v79, s[24:25]
	v_ldexp_f32 v28, v5, v95
	v_cvt_pk_bf16_f32 v5, v18, v19
	v_cndmask_b32_e32 v18, 0, v79, vcc
	v_ldexp_f32 v18, v13, v18
	v_subrev_u32_e32 v13, 51, v69
	v_cndmask_b32_e64 v85, 0, v79, s[8:9]
	v_cndmask_b32_e64 v86, 0, v79, s[10:11]
	v_cndmask_b32_e64 v87, 0, v79, s[12:13]
	v_cndmask_b32_e64 v88, 0, v79, s[14:15]
	s_waitcnt lgkmcnt(1)
	v_mfma_f32_16x16x32_bf16 v[22:25], v[38:41], v[48:51], v[30:33]
	v_cvt_f32_i32_e32 v13, v13
	v_ldexp_f32 v34, v100, v85
	v_ldexp_f32 v35, v101, v86
	v_ldexp_f32 v36, v102, v87
	v_ldexp_f32 v37, v103, v88
	v_pk_mul_f32 v[6:7], v[34:35], v[6:7]
	v_pk_mul_f32 v[30:31], v[36:37], v[8:9]
	v_add_u32_e32 v75, 0x8800, v21
	v_cvt_pk_bf16_f32 v4, v10, v11
	v_add_u32_e32 v77, 0x9000, v21
	v_cvt_pk_bf16_f32 v6, v6, v7
	v_cvt_pk_bf16_f32 v7, v30, v31
	v_add_u32_e32 v93, 0xa000, v21
	v_add_u32_e32 v94, 0xa800, v21
	v_add_u32_e32 v69, 0xb000, v21
	v_add_u32_e32 v95, 0xb800, v21
	v_add_u32_e32 v96, 0xc000, v21
	v_pk_mul_f32 v[22:23], v[28:29], v[22:23]
	ds_read2_b64 v[0:3], v75 offset1:4
	ds_read2_b64 v[8:11], v77 offset0:32 offset1:36
	ds_read2_b64 v[26:29], v93 offset0:96 offset1:100
	ds_read2_b64 v[30:33], v94 offset0:128 offset1:132
	s_waitcnt lgkmcnt(4)
	v_mfma_f32_16x16x32_bf16 v[34:37], v[14:17], v[4:7], 0
	ds_read2_b64 v[14:17], v69 offset0:160 offset1:164
	v_mul_f32_e64 v19, |v13|, v83
	ds_read2_b64 v[38:41], v95 offset0:192 offset1:196
	ds_read2_b64 v[42:45], v96 offset0:224 offset1:228
	v_cmp_gt_f32_e32 vcc, s53, v19
	s_waitcnt lgkmcnt(6)
	v_mfma_f32_16x16x32_bf16 v[0:3], v[0:3], v[4:7], 0
	v_cvt_pk_bf16_f32 v89, v90, v91
	v_cndmask_b32_e32 v19, 0, v78, vcc
	v_fma_f32 v13, |v13|, v83, v19
	v_exp_f32_e32 v13, v13
	v_cndmask_b32_e32 v19, 0, v79, vcc
	s_waitcnt lgkmcnt(5)
	v_mfma_f32_16x16x32_bf16 v[8:11], v[8:11], v[4:7], 0
	v_cvt_pk_bf16_f32 v90, v22, v23
	v_ldexp_f32 v19, v13, v19
	v_pk_mul_f32 v[18:19], v[18:19], v[24:25]
	s_waitcnt lgkmcnt(4)
	v_mfma_f32_16x16x32_bf16 v[26:29], v[26:29], v[4:7], 0
	ds_read2_b64 v[22:25], v92 offset0:72 offset1:76
	v_cvt_pk_bf16_f32 v88, v46, v47
	v_cvt_pk_bf16_f32 v91, v18, v19
	s_waitcnt lgkmcnt(4)
	v_mfma_f32_16x16x32_bf16 v[30:33], v[30:33], v[4:7], 0
	v_ashrrev_i32_e32 v13, 31, v12
	v_lshlrev_b64 v[12:13], 15, v[12:13]
	v_lshlrev_b32_e32 v20, 8, v20
	s_waitcnt lgkmcnt(3)
	v_mfma_f32_16x16x32_bf16 v[84:87], v[14:17], v[4:7], 0
	ds_read2_b64 v[14:17], v75 offset0:8 offset1:12
	v_mov_b32_e32 v75, v65
	v_mov_b32_e32 v21, v65
	s_waitcnt lgkmcnt(3)
	v_mfma_f32_16x16x32_bf16 v[38:41], v[38:41], v[4:7], 0
	v_readlane_b32 s4, v255, 2
	v_readlane_b32 s6, v255, 4
	v_readlane_b32 s7, v255, 5
	s_waitcnt lgkmcnt(2)
	v_mfma_f32_16x16x32_bf16 v[42:45], v[42:45], v[4:7], 0
	ds_read2_b64 v[4:7], v77 offset0:40 offset1:44
	v_mov_b32_e32 v77, v65
	v_readlane_b32 s5, v255, 3
	s_waitcnt lgkmcnt(1)
	v_mfma_f32_16x16x32_bf16 v[16:19], v[14:17], v[88:91], v[0:3]
	v_readlane_b32 s8, v255, 6
	v_readlane_b32 s9, v255, 7
	v_readlane_b32 s10, v255, 8
	s_waitcnt lgkmcnt(0)
	v_mfma_f32_16x16x32_bf16 v[0:3], v[4:7], v[88:91], v[8:11]
	v_readlane_b32 s11, v255, 9
	s_nop 1
	ds_read2_b64 v[8:11], v93 offset0:104 offset1:108
	v_readlane_b32 s12, v255, 10
	v_mfma_f32_16x16x32_bf16 v[4:7], v[22:25], v[88:91], v[34:37]
	ds_read2_b64 v[22:25], v94 offset0:136 offset1:140
	v_readlane_b32 s13, v255, 11
	v_readlane_b32 s14, v255, 12
	s_waitcnt lgkmcnt(1)
	v_mfma_f32_16x16x32_bf16 v[8:11], v[8:11], v[88:91], v[26:29]
	s_nop 2
	v_lshl_add_u64 v[26:27], s[42:43], 0, v[12:13]
	v_lshl_add_u64 v[26:27], v[26:27], 0, v[74:75]
	v_lshl_add_u64 v[108:109], v[26:27], 0, v[20:21]
	s_waitcnt lgkmcnt(0)
	v_mfma_f32_16x16x32_bf16 v[12:15], v[22:25], v[88:91], v[30:33]
	ds_read2_b64 v[22:25], v69 offset0:168 offset1:172
	v_add_co_u32_e32 v134, vcc, s63, v108
	s_nop 1
	v_addc_co_u32_e32 v135, vcc, 0, v109, vcc
	v_add_co_u32_e32 v136, vcc, s64, v108
	s_nop 1
	v_addc_co_u32_e32 v137, vcc, 0, v109, vcc
	v_add_co_u32_e32 v138, vcc, s65, v108
	s_nop 1
	v_addc_co_u32_e32 v139, vcc, 0, v109, vcc
	v_add_co_u32_e32 v140, vcc, s66, v108
	s_nop 1
	v_addc_co_u32_e32 v141, vcc, 0, v109, vcc
	v_add_co_u32_e32 v142, vcc, s67, v108
	s_nop 1
	v_addc_co_u32_e32 v143, vcc, 0, v109, vcc
	v_add_co_u32_e32 v150, vcc, s68, v108
	s_nop 1
	v_addc_co_u32_e32 v151, vcc, 0, v109, vcc
	v_add_co_u32_e32 v152, vcc, s69, v108
	s_nop 1
	v_addc_co_u32_e32 v153, vcc, 0, v109, vcc
	global_load_dwordx4 v[160:163], v[108:109], off
	global_load_dwordx4 v[164:167], v[108:109], off offset:64
	global_load_dwordx4 v[168:171], v[108:109], off offset:128
	global_load_dwordx4 v[172:175], v[108:109], off offset:192
	global_load_dwordx4 v[176:179], v[134:135], off
	global_load_dwordx4 v[180:183], v[134:135], off offset:64
	global_load_dwordx4 v[184:187], v[134:135], off offset:128
	global_load_dwordx4 v[188:191], v[134:135], off offset:192
	global_load_dwordx4 v[192:195], v[136:137], off
	global_load_dwordx4 v[196:199], v[136:137], off offset:64
	global_load_dwordx4 v[200:203], v[136:137], off offset:128
	global_load_dwordx4 v[204:207], v[136:137], off offset:192
	global_load_dwordx4 v[208:211], v[138:139], off
	global_load_dwordx4 v[212:215], v[138:139], off offset:64
	global_load_dwordx4 v[216:219], v[138:139], off offset:128
	global_load_dwordx4 v[220:223], v[138:139], off offset:192
	global_load_dwordx4 v[224:227], v[140:141], off
	global_load_dwordx4 v[228:231], v[140:141], off offset:64
	global_load_dwordx4 v[232:235], v[140:141], off offset:128
	global_load_dwordx4 v[236:239], v[140:141], off offset:192
	global_load_dwordx4 v[240:243], v[142:143], off
	global_load_dwordx4 v[244:247], v[142:143], off offset:64
	global_load_dwordx4 v[248:251], v[142:143], off offset:128
	ds_read2_b64 v[30:33], v95 offset0:200 offset1:204
	s_waitcnt lgkmcnt(0)
	v_mfma_f32_16x16x32_bf16 v[20:23], v[22:25], v[88:91], v[84:87]
	v_ashrrev_i32_e32 v69, 31, v68
	v_mfma_f32_16x16x32_bf16 v[84:87], v[30:33], v[88:91], v[38:41]
	ds_read2_b64 v[30:33], v96 offset0:232 offset1:236
	s_waitcnt lgkmcnt(0)
	v_mfma_f32_16x16x32_bf16 v[88:91], v[30:33], v[88:91], v[42:45]
	s_nop 0
	s_waitcnt lgkmcnt(0)
	global_load_dwordx4 v[96:99], v[142:143], off offset:192
	global_load_dwordx4 v[100:103], v[150:151], off
	global_load_dwordx4 v[104:107], v[150:151], off offset:64
	s_waitcnt vmcnt(22)
	v_mfma_f32_16x16x32_bf16 v[36:39], v[160:163], v[56:59], 0
	v_mfma_f32_16x16x32_bf16 v[36:39], v[164:167], v[60:63], v[36:39]
	v_mfma_f32_16x16x32_bf16 v[36:39], v[168:171], v[52:55], v[36:39]
	v_mfma_f32_16x16x32_bf16 v[36:39], v[172:175], v[48:51], v[36:39]
	global_load_dwordx4 v[160:163], v[150:151], off offset:128
	global_load_dwordx4 v[164:167], v[150:151], off offset:192
	global_load_dwordx4 v[168:171], v[152:153], off
	global_load_dwordx4 v[172:175], v[152:153], off offset:64
	s_waitcnt vmcnt(22)
	v_mfma_f32_16x16x32_bf16 v[24:27], v[176:179], v[56:59], 0
	v_mfma_f32_16x16x32_bf16 v[24:27], v[180:183], v[60:63], v[24:27]
	v_mfma_f32_16x16x32_bf16 v[24:27], v[184:187], v[52:55], v[24:27]
	v_mfma_f32_16x16x32_bf16 v[24:27], v[188:191], v[48:51], v[24:27]
	global_load_dwordx4 v[176:179], v[152:153], off offset:128
	global_load_dwordx4 v[180:183], v[152:153], off offset:192
	s_waitcnt vmcnt(20)
	v_mfma_f32_16x16x32_bf16 v[28:31], v[192:195], v[56:59], 0
	v_mfma_f32_16x16x32_bf16 v[28:31], v[196:199], v[60:63], v[28:31]
	v_mfma_f32_16x16x32_bf16 v[28:31], v[200:203], v[52:55], v[28:31]
	v_mfma_f32_16x16x32_bf16 v[28:31], v[204:207], v[48:51], v[28:31]
	s_waitcnt vmcnt(16)
	v_mfma_f32_16x16x32_bf16 v[32:35], v[208:211], v[56:59], 0
	v_mfma_f32_16x16x32_bf16 v[32:35], v[212:215], v[60:63], v[32:35]
	v_mfma_f32_16x16x32_bf16 v[32:35], v[216:219], v[52:55], v[32:35]
	v_mfma_f32_16x16x32_bf16 v[32:35], v[220:223], v[48:51], v[32:35]
	s_waitcnt vmcnt(12)
	v_mfma_f32_16x16x32_bf16 v[40:43], v[224:227], v[56:59], 0
	v_mfma_f32_16x16x32_bf16 v[40:43], v[228:231], v[60:63], v[40:43]
	v_mfma_f32_16x16x32_bf16 v[40:43], v[232:235], v[52:55], v[40:43]
	v_mfma_f32_16x16x32_bf16 v[40:43], v[236:239], v[48:51], v[40:43]
	s_waitcnt vmcnt(8)
	v_mfma_f32_16x16x32_bf16 v[44:47], v[240:243], v[56:59], 0
	v_mfma_f32_16x16x32_bf16 v[44:47], v[244:247], v[60:63], v[44:47]
	v_mfma_f32_16x16x32_bf16 v[44:47], v[248:251], v[52:55], v[44:47]
	v_mfma_f32_16x16x32_bf16 v[44:47], v[96:99], v[48:51], v[44:47]
	s_waitcnt vmcnt(4)
	v_mfma_f32_16x16x32_bf16 v[92:95], v[100:103], v[56:59], 0
	v_mfma_f32_16x16x32_bf16 v[92:95], v[104:107], v[60:63], v[92:95]
	v_mfma_f32_16x16x32_bf16 v[92:95], v[160:163], v[52:55], v[92:95]
	v_mfma_f32_16x16x32_bf16 v[92:95], v[164:167], v[48:51], v[92:95]
	s_waitcnt vmcnt(0)
	v_mfma_f32_16x16x32_bf16 v[56:59], v[168:171], v[56:59], 0
	v_mfma_f32_16x16x32_bf16 v[56:59], v[172:175], v[60:63], v[56:59]
	v_mfma_f32_16x16x32_bf16 v[52:55], v[176:179], v[52:55], v[56:59]
	v_mfma_f32_16x16x32_bf16 v[48:51], v[180:183], v[48:51], v[52:55]
	v_readlane_b32 s15, v255, 13
	v_readlane_b32 s16, v255, 14
	v_readlane_b32 s17, v255, 15
	v_readlane_b32 s18, v255, 16
	v_readlane_b32 s19, v255, 17
	s_waitcnt lgkmcnt(0)
	s_nop 5
	s_waitcnt lgkmcnt(0)
	s_nop 2
	s_nop 2
	s_waitcnt lgkmcnt(0)
	s_nop 0
	s_nop 3
	s_waitcnt lgkmcnt(0)
	s_waitcnt lgkmcnt(0)
	s_waitcnt lgkmcnt(0)
	s_nop 0
	s_waitcnt lgkmcnt(0)
	s_nop 0
	s_waitcnt lgkmcnt(0)
	s_waitcnt lgkmcnt(0)
	s_nop 0
	s_waitcnt lgkmcnt(0)
	v_lshl_add_u64 v[100:101], v[68:69], 0, v[76:77]
	v_mad_u64_u32 v[60:61], s[0:1], v100, s57, v[66:67]
	v_mad_i32_i24 v61, v101, s57, v61
	v_lshl_add_u64 v[60:61], v[60:61], 0, v[72:73]
	v_lshl_add_u64 v[102:103], v[60:61], 0, v[64:65]
	v_add_co_u32_e32 v60, vcc, s63, v102
	s_waitcnt lgkmcnt(0)
	v_addc_co_u32_e32 v61, vcc, 0, v103, vcc
	flat_load_dwordx2 v[68:69], v[60:61] offset:512
	s_nop 0
	v_add_u32_e32 v56, 1, v76
	v_cvt_f32_ubyte0_e32 v56, v56
	v_mul_f32_e32 v57, v83, v56
	v_cmp_gt_f32_e32 vcc, s53, v57
	s_waitcnt vmcnt(0) lgkmcnt(0)
	v_lshlrev_b32_e32 v77, 16, v68
	v_cndmask_b32_e32 v57, 0, v78, vcc
	v_fmac_f32_e32 v57, v83, v56
	v_exp_f32_e32 v56, v57
	v_cndmask_b32_e32 v52, 0, v79, vcc
	v_and_b32_e32 v68, 0xffff0000, v68
	v_cmp_lt_i32_e32 vcc, v157, v156
	v_ldexp_f32 v62, v56, v52
	v_pk_fma_f32 v[58:59], v[62:63], v[50:51], v[90:91] op_sel_hi:[0,1,1]
	v_lshlrev_b64 v[50:51], 11, v[100:101]
	v_lshl_add_u64 v[50:51], s[30:31], 0, v[50:51]
	v_lshl_add_u64 v[52:53], v[50:51], 0, v[72:73]
	v_mul_f32_e32 v72, 0xbfb8aa3b, v77
	v_pk_fma_f32 v[54:55], v[62:63], v[92:93], v[84:85] op_sel_hi:[0,1,1]
	v_exp_f32_e32 v84, v72
	v_mul_f32_e32 v72, 0xbfb8aa3b, v68
	v_exp_f32_e32 v85, v72
	v_pk_fma_f32 v[60:61], v[62:63], v[48:49], v[88:89] op_sel_hi:[0,1,1]
	v_cndmask_b32_e32 v48, v155, v157, vcc
	v_cmp_lt_i32_e32 vcc, v158, v156
	v_lshlrev_b32_e32 v76, 2, v48
	v_pk_fma_f32 v[56:57], v[62:63], v[94:95], v[86:87] op_sel_hi:[0,1,1]
	v_cndmask_b32_e32 v48, v155, v158, vcc
	v_lshlrev_b32_e32 v63, 2, v48
	v_pk_fma_f32 v[18:19], v[62:63], v[38:39], v[18:19] op_sel_hi:[0,1,1]
	v_pk_add_f32 v[38:39], v[84:85], 1.0 op_sel_hi:[1,0]
	v_lshlrev_b32_e32 v83, 16, v69
	v_and_b32_e32 v86, 0xffff0000, v69
	v_div_scale_f32 v69, s[0:1], v39, v39, v68
	v_rcp_f32_e32 v84, v69
	v_pk_fma_f32 v[16:17], v[62:63], v[36:37], v[16:17] op_sel_hi:[0,1,1]
	v_add_f32_e32 v36, 0, v16
	v_add_f32_e32 v85, v17, v36
	v_fma_f32 v36, -v69, v84, 1.0
	v_fmac_f32_e32 v84, v36, v84
	v_div_scale_f32 v36, vcc, v68, v39, v68
	v_mul_f32_e32 v37, v36, v84
	v_fma_f32 v87, -v69, v37, v36
	v_fmac_f32_e32 v37, v87, v84
	v_div_scale_f32 v87, s[0:1], v38, v38, v77
	v_rcp_f32_e32 v88, v87
	v_fma_f32 v36, -v69, v37, v36
	v_div_fmas_f32 v36, v36, v84, v37
	v_div_fixup_f32 v37, v36, v39, v68
	v_fma_f32 v36, -v87, v88, 1.0
	v_fmac_f32_e32 v88, v36, v88
	v_div_scale_f32 v36, vcc, v77, v38, v77
	v_mul_f32_e32 v39, v36, v88
	v_fma_f32 v68, -v87, v39, v36
	v_fmac_f32_e32 v39, v68, v88
	v_fma_f32 v36, -v87, v39, v36
	v_div_fmas_f32 v36, v36, v88, v39
	v_div_fixup_f32 v36, v36, v38, v77
	v_add_f32_e32 v38, v18, v85
	v_add_f32_e32 v38, v19, v38
	v_pk_fma_f32 v[0:1], v[62:63], v[24:25], v[0:1] op_sel_hi:[0,1,1]
	v_add_f32_e32 v24, v38, v0
	v_pk_fma_f32 v[2:3], v[62:63], v[26:27], v[2:3] op_sel_hi:[0,1,1]
	v_add_f32_e32 v24, v1, v24
	v_add_f32_e32 v24, v2, v24
	v_add_f32_e32 v24, v3, v24
	v_pk_fma_f32 v[4:5], v[62:63], v[28:29], v[4:5] op_sel_hi:[0,1,1]
	v_add_f32_e32 v24, v24, v4
	v_pk_fma_f32 v[6:7], v[62:63], v[30:31], v[6:7] op_sel_hi:[0,1,1]
	v_add_f32_e32 v24, v5, v24
	v_add_f32_e32 v24, v6, v24
	v_add_f32_e32 v24, v7, v24
	v_pk_fma_f32 v[8:9], v[62:63], v[32:33], v[8:9] op_sel_hi:[0,1,1]
	v_add_f32_e32 v24, v24, v8
	v_pk_fma_f32 v[10:11], v[62:63], v[34:35], v[10:11] op_sel_hi:[0,1,1]
	v_add_f32_e32 v24, v9, v24
	v_add_f32_e32 v24, v10, v24
	v_add_f32_e32 v24, v11, v24
	v_pk_fma_f32 v[12:13], v[62:63], v[40:41], v[12:13] op_sel_hi:[0,1,1]
	v_add_f32_e32 v24, v24, v12
	v_pk_fma_f32 v[14:15], v[62:63], v[42:43], v[14:15] op_sel_hi:[0,1,1]
	v_add_f32_e32 v24, v13, v24
	v_lshl_add_u64 v[48:49], v[70:71], 2, s[6:7]
	v_add_f32_e32 v24, v14, v24
	v_lshl_add_u64 v[48:49], v[48:49], 0, v[74:75]
	v_add_f32_e32 v28, v15, v24
	v_pk_fma_f32 v[26:27], v[62:63], v[44:45], v[20:21] op_sel_hi:[0,1,1]
	global_load_dwordx4 v[72:75], v[48:49], off
	v_add_f32_e32 v20, v28, v26
	v_pk_fma_f32 v[24:25], v[62:63], v[46:47], v[22:23] op_sel_hi:[0,1,1]
	v_add_f32_e32 v20, v27, v20
	v_add_f32_e32 v20, v24, v20
	v_add_f32_e32 v20, v25, v20
	v_add_f32_e32 v20, v20, v54
	v_add_f32_e32 v20, v55, v20
	v_mul_f32_e32 v68, 0xbfb8aa3b, v83
	v_mul_f32_e32 v69, 0xbfb8aa3b, v86
	v_add_f32_e32 v20, v56, v20
	v_exp_f32_e32 v68, v68
	v_exp_f32_e32 v69, v69
	v_add_f32_e32 v20, v57, v20
	v_add_f32_e32 v20, v20, v60
	v_add_f32_e32 v20, v61, v20
	v_add_f32_e32 v20, v58, v20
	v_pk_add_f32 v[68:69], v[68:69], 1.0 op_sel_hi:[1,0]
	v_add_f32_e32 v20, v59, v20
	v_div_scale_f32 v39, s[0:1], v69, v69, v86
	ds_bpermute_b32 v21, v76, v20
	v_rcp_f32_e32 v84, v39
	v_lshl_add_u64 v[50:51], v[102:103], 0, s[46:47]
	flat_load_dwordx2 v[70:71], v[50:51] offset:224
	flat_load_dwordx2 v[30:31], v[50:51] offset:32
	v_fma_f32 v77, -v39, v84, 1.0
	s_waitcnt lgkmcnt(0)
	v_add_f32_e32 v20, v20, v21
	v_fmac_f32_e32 v84, v77, v84
	v_div_scale_f32 v77, vcc, v86, v69, v86
	ds_bpermute_b32 v21, v63, v20
	v_mul_f32_e32 v85, v77, v84
	v_fma_f32 v87, -v39, v85, v77
	v_fmac_f32_e32 v85, v87, v84
	v_fma_f32 v22, -v39, v85, v77
	v_div_fmas_f32 v22, v22, v84, v85
	s_waitcnt lgkmcnt(0)
	v_add_f32_e32 v20, v20, v21
	v_div_fixup_f32 v29, v22, v69, v86
	v_mul_f32_e32 v28, 0x3c000000, v20
	v_pk_add_f32 v[32:33], v[16:17], v[28:29] op_sel_hi:[1,0] neg_lo:[0,1] neg_hi:[0,1]
	v_pk_add_f32 v[38:39], v[18:19], v[28:29] op_sel_hi:[1,0] neg_lo:[0,1] neg_hi:[0,1]
	v_pk_mul_f32 v[34:35], v[32:33], v[32:33]
	v_pk_mul_f32 v[40:41], v[38:39], v[38:39]
	v_pk_add_f32 v[42:43], v[0:1], v[28:29] op_sel_hi:[1,0] neg_lo:[0,1] neg_hi:[0,1]
	v_pk_add_f32 v[46:47], v[2:3], v[28:29] op_sel_hi:[1,0] neg_lo:[0,1] neg_hi:[0,1]
	v_pk_add_f32 v[84:85], v[4:5], v[28:29] op_sel_hi:[1,0] neg_lo:[0,1] neg_hi:[0,1]
	v_pk_add_f32 v[88:89], v[6:7], v[28:29] op_sel_hi:[1,0] neg_lo:[0,1] neg_hi:[0,1]
	v_pk_add_f32 v[22:23], v[8:9], v[28:29] op_sel_hi:[1,0] neg_lo:[0,1] neg_hi:[0,1]
	v_pk_add_f32 v[20:21], v[10:11], v[28:29] op_sel_hi:[1,0] neg_lo:[0,1] neg_hi:[0,1]
	v_pk_add_f32 v[18:19], v[12:13], v[28:29] op_sel_hi:[1,0] neg_lo:[0,1] neg_hi:[0,1]
	v_pk_add_f32 v[16:17], v[14:15], v[28:29] op_sel_hi:[1,0] neg_lo:[0,1] neg_hi:[0,1]
	v_pk_add_f32 v[14:15], v[26:27], v[28:29] op_sel_hi:[1,0] neg_lo:[0,1] neg_hi:[0,1]
	v_pk_add_f32 v[12:13], v[24:25], v[28:29] op_sel_hi:[1,0] neg_lo:[0,1] neg_hi:[0,1]
	v_pk_add_f32 v[4:5], v[60:61], v[28:29] op_sel_hi:[1,0] neg_lo:[0,1] neg_hi:[0,1]
	v_pk_add_f32 v[0:1], v[58:59], v[28:29] op_sel_hi:[1,0] neg_lo:[0,1] neg_hi:[0,1]
	v_pk_add_f32 v[8:9], v[56:57], v[28:29] op_sel_hi:[1,0] neg_lo:[0,1] neg_hi:[0,1]
	v_pk_add_f32 v[10:11], v[54:55], v[28:29] op_sel_hi:[1,0] neg_lo:[0,1] neg_hi:[0,1]
	v_add_f32_e32 v28, v34, v35
	v_add_f32_e32 v28, v40, v28
	v_pk_mul_f32 v[44:45], v[42:43], v[42:43]
	v_add_f32_e32 v28, v41, v28
	v_add_f32_e32 v28, v44, v28
	v_pk_mul_f32 v[2:3], v[46:47], v[46:47]
	v_add_f32_e32 v28, v45, v28
	v_add_f32_e32 v2, v2, v28
	v_pk_mul_f32 v[86:87], v[84:85], v[84:85]
	v_add_f32_e32 v2, v3, v2
	v_add_f32_e32 v2, v86, v2
	v_pk_mul_f32 v[6:7], v[88:89], v[88:89]
	v_add_f32_e32 v2, v87, v2
	v_add_f32_e32 v2, v6, v2
	v_pk_mul_f32 v[90:91], v[22:23], v[22:23]
	v_add_f32_e32 v2, v7, v2
	v_add_f32_e32 v2, v90, v2
	v_pk_mul_f32 v[92:93], v[20:21], v[20:21]
	v_add_f32_e32 v2, v91, v2
	v_add_f32_e32 v2, v92, v2
	v_pk_mul_f32 v[94:95], v[18:19], v[18:19]
	v_add_f32_e32 v2, v93, v2
	v_add_f32_e32 v2, v94, v2
	v_pk_mul_f32 v[96:97], v[16:17], v[16:17]
	v_add_f32_e32 v2, v95, v2
	v_add_f32_e32 v2, v96, v2
	v_pk_mul_f32 v[26:27], v[14:15], v[14:15]
	v_add_f32_e32 v2, v97, v2
	v_add_f32_e32 v2, v26, v2
	v_pk_mul_f32 v[24:25], v[12:13], v[12:13]
	v_add_f32_e32 v2, v27, v2
	v_add_f32_e32 v2, v24, v2
	v_pk_mul_f32 v[54:55], v[10:11], v[10:11]
	v_add_f32_e32 v2, v25, v2
	v_add_f32_e32 v2, v54, v2
	v_pk_mul_f32 v[56:57], v[8:9], v[8:9]
	v_add_f32_e32 v2, v55, v2
	v_add_f32_e32 v2, v56, v2
	v_pk_mul_f32 v[60:61], v[4:5], v[4:5]
	v_add_f32_e32 v2, v57, v2
	v_add_f32_e32 v2, v60, v2
	v_pk_mul_f32 v[58:59], v[0:1], v[0:1]
	v_add_f32_e32 v2, v61, v2
	v_add_f32_e32 v2, v58, v2
	v_add_f32_e32 v2, v59, v2
	ds_bpermute_b32 v3, v76, v2
	v_div_scale_f32 v62, s[0:1], v68, v68, v83
	v_rcp_f32_e32 v69, v62
	s_waitcnt vmcnt(0)
	v_lshlrev_b32_e32 v40, 16, v31
	s_waitcnt lgkmcnt(0)
	v_add_f32_e32 v2, v2, v3
	ds_bpermute_b32 v3, v63, v2
	v_fma_f32 v6, -v62, v69, 1.0
	v_fmac_f32_e32 v69, v6, v69
	v_div_scale_f32 v6, vcc, v83, v68, v83
	s_waitcnt lgkmcnt(0)
	v_add_f32_e32 v2, v2, v3
	v_fmamk_f32 v2, v2, 0x3c000000, v81
	v_mul_f32_e32 v7, v6, v69
	v_mul_f32_e32 v3, 0x4b800000, v2
	v_cmp_gt_f32_e64 s[0:1], s54, v2
	v_fma_f32 v24, -v62, v7, v6
	v_fmac_f32_e32 v7, v24, v69
	v_cndmask_b32_e64 v2, v2, v3, s[0:1]
	v_rsq_f32_e32 v24, v2
	v_fma_f32 v6, -v62, v7, v6
	v_div_fmas_f32 v2, v6, v69, v7
	v_div_fixup_f32 v28, v2, v68, v83
	v_mul_f32_e32 v6, 0x45800000, v24
	v_cndmask_b32_e64 v6, v24, v6, s[0:1]
	v_pk_mul_f32 v[24:25], v[32:33], v[6:7] op_sel_hi:[1,0]
	v_pk_mul_f32 v[26:27], v[38:39], v[6:7] op_sel_hi:[1,0]
	v_pk_mul_f32 v[24:25], v[72:73], v[24:25]
	v_pk_mul_f32 v[26:27], v[74:75], v[26:27]
	v_pk_mul_f32 v[24:25], v[36:37], v[24:25]
	v_pk_mul_f32 v[26:27], v[28:29], v[26:27]
	v_lshl_add_u64 v[2:3], v[52:53], 0, v[64:65]
	v_cvt_pk_bf16_f32 v24, v24, v25
	v_cvt_pk_bf16_f32 v25, v26, v27
	flat_store_dwordx2 v[2:3], v[24:25]
	global_load_dwordx4 v[24:27], v[48:49], off offset:64
	s_nop 0
	flat_load_dwordx2 v[28:29], v[50:51] offset:64
	flat_load_dwordx2 v[32:33], v[50:51] offset:96
	flat_load_dwordx2 v[34:35], v[50:51] offset:128
	v_lshlrev_b32_e32 v7, 16, v30
	v_and_b32_e32 v30, 0xffff0000, v30
	v_mul_f32_e32 v36, 0xbfb8aa3b, v7
	v_mul_f32_e32 v37, 0xbfb8aa3b, v30
	v_exp_f32_e32 v36, v36
	v_exp_f32_e32 v37, v37
	v_and_b32_e32 v41, 0xffff0000, v31
	v_pk_add_f32 v[36:37], v[36:37], 1.0 op_sel_hi:[1,0]
	s_nop 0
	v_div_scale_f32 v38, s[0:1], v37, v37, v30
	v_rcp_f32_e32 v39, v38
	s_nop 0
	v_fma_f32 v31, -v38, v39, 1.0
	v_fmac_f32_e32 v39, v31, v39
	v_div_scale_f32 v31, vcc, v30, v37, v30
	v_mul_f32_e32 v44, v31, v39
	v_fma_f32 v45, -v38, v44, v31
	v_fmac_f32_e32 v44, v45, v39
	v_div_scale_f32 v45, s[0:1], v36, v36, v7
	v_rcp_f32_e32 v52, v45
	v_fma_f32 v31, -v38, v44, v31
	v_div_fmas_f32 v31, v31, v39, v44
	v_mul_f32_e32 v38, 0xbfb8aa3b, v40
	v_mul_f32_e32 v39, 0xbfb8aa3b, v41
	v_exp_f32_e32 v38, v38
	v_exp_f32_e32 v39, v39
	v_div_fixup_f32 v31, v31, v37, v30
	v_fma_f32 v30, -v45, v52, 1.0
	v_fmac_f32_e32 v52, v30, v52
	v_div_scale_f32 v30, vcc, v7, v36, v7
	v_mul_f32_e32 v37, v30, v52
	v_fma_f32 v44, -v45, v37, v30
	v_pk_add_f32 v[38:39], v[38:39], 1.0 op_sel_hi:[1,0]
	v_fmac_f32_e32 v37, v44, v52
	v_div_scale_f32 v44, s[0:1], v39, v39, v41
	v_fma_f32 v30, -v45, v37, v30
	v_rcp_f32_e32 v45, v44
	v_div_fmas_f32 v30, v30, v52, v37
	v_div_fixup_f32 v30, v30, v36, v7
	v_fma_f32 v7, -v44, v45, 1.0
	v_fmac_f32_e32 v45, v7, v45
	v_div_scale_f32 v7, vcc, v41, v39, v41
	v_mul_f32_e32 v36, v7, v45
	v_fma_f32 v37, -v44, v36, v7
	v_fmac_f32_e32 v36, v37, v45
	v_fma_f32 v7, -v44, v36, v7
	v_div_scale_f32 v44, s[0:1], v38, v38, v40
	v_rcp_f32_e32 v52, v44
	v_div_fmas_f32 v7, v7, v45, v36
	v_div_fixup_f32 v37, v7, v39, v41
	v_fma_f32 v7, -v44, v52, 1.0
	v_fmac_f32_e32 v52, v7, v52
	v_div_scale_f32 v7, vcc, v40, v38, v40
	v_mul_f32_e32 v36, v7, v52
	v_fma_f32 v39, -v44, v36, v7
	v_fmac_f32_e32 v36, v39, v52
	v_fma_f32 v7, -v44, v36, v7
	v_div_fmas_f32 v7, v7, v52, v36
	v_div_fixup_f32 v36, v7, v38, v40
	v_pk_mul_f32 v[38:39], v[42:43], v[6:7] op_sel_hi:[1,0]
	s_waitcnt vmcnt(0)
	v_pk_mul_f32 v[24:25], v[24:25], v[38:39]
	s_nop 0
	v_pk_mul_f32 v[24:25], v[30:31], v[24:25]
	v_pk_mul_f32 v[30:31], v[46:47], v[6:7] op_sel_hi:[1,0]
	v_cvt_pk_bf16_f32 v24, v24, v25
	v_pk_mul_f32 v[26:27], v[26:27], v[30:31]
	s_waitcnt lgkmcnt(0)
	v_lshlrev_b32_e32 v7, 16, v28
	v_pk_mul_f32 v[26:27], v[36:37], v[26:27]
	v_and_b32_e32 v28, 0xffff0000, v28
	v_cvt_pk_bf16_f32 v25, v26, v27
	flat_store_dwordx2 v[2:3], v[24:25] offset:32
	global_load_dwordx4 v[24:27], v[48:49], off offset:128
	v_mul_f32_e32 v30, 0xbfb8aa3b, v7
	v_mul_f32_e32 v31, 0xbfb8aa3b, v28
	v_exp_f32_e32 v30, v30
	v_exp_f32_e32 v31, v31
	v_lshlrev_b32_e32 v38, 16, v29
	v_and_b32_e32 v39, 0xffff0000, v29
	v_pk_add_f32 v[30:31], v[30:31], 1.0 op_sel_hi:[1,0]
	s_nop 0
	v_div_scale_f32 v36, s[0:1], v31, v31, v28
	v_rcp_f32_e32 v37, v36
	s_nop 0
	v_fma_f32 v29, -v36, v37, 1.0
	v_fmac_f32_e32 v37, v29, v37
	v_div_scale_f32 v29, vcc, v28, v31, v28
	v_mul_f32_e32 v40, v29, v37
	v_fma_f32 v41, -v36, v40, v29
	v_fmac_f32_e32 v40, v41, v37
	v_div_scale_f32 v41, s[0:1], v30, v30, v7
	v_rcp_f32_e32 v42, v41
	v_fma_f32 v29, -v36, v40, v29
	v_div_fmas_f32 v29, v29, v37, v40
	v_mul_f32_e32 v36, 0xbfb8aa3b, v38
	v_mul_f32_e32 v37, 0xbfb8aa3b, v39
	v_exp_f32_e32 v36, v36
	v_exp_f32_e32 v37, v37
	v_div_fixup_f32 v29, v29, v31, v28
	v_fma_f32 v28, -v41, v42, 1.0
	v_fmac_f32_e32 v42, v28, v42
	v_div_scale_f32 v28, vcc, v7, v30, v7
	v_mul_f32_e32 v31, v28, v42
	v_fma_f32 v40, -v41, v31, v28
	v_pk_add_f32 v[36:37], v[36:37], 1.0 op_sel_hi:[1,0]
	v_fmac_f32_e32 v31, v40, v42
	v_div_scale_f32 v40, s[0:1], v37, v37, v39
	v_fma_f32 v28, -v41, v31, v28
	v_rcp_f32_e32 v41, v40
	v_div_fmas_f32 v28, v28, v42, v31
	v_div_fixup_f32 v28, v28, v30, v7
	v_fma_f32 v7, -v40, v41, 1.0
	v_fmac_f32_e32 v41, v7, v41
	v_div_scale_f32 v7, vcc, v39, v37, v39
	v_mul_f32_e32 v30, v7, v41
	v_fma_f32 v31, -v40, v30, v7
	v_fmac_f32_e32 v30, v31, v41
	v_fma_f32 v7, -v40, v30, v7
	v_div_scale_f32 v40, s[0:1], v36, v36, v38
	v_rcp_f32_e32 v42, v40
	v_div_fmas_f32 v7, v7, v41, v30
	v_div_fixup_f32 v31, v7, v37, v39
	v_fma_f32 v7, -v40, v42, 1.0
	v_fmac_f32_e32 v42, v7, v42
	v_div_scale_f32 v7, vcc, v38, v36, v38
	v_mul_f32_e32 v30, v7, v42
	v_fma_f32 v37, -v40, v30, v7
	v_fmac_f32_e32 v30, v37, v42
	v_fma_f32 v7, -v40, v30, v7
	v_div_fmas_f32 v7, v7, v42, v30
	v_div_fixup_f32 v30, v7, v36, v38
	v_pk_mul_f32 v[36:37], v[84:85], v[6:7] op_sel_hi:[1,0]
	s_waitcnt vmcnt(0)
	v_pk_mul_f32 v[24:25], v[24:25], v[36:37]
	s_nop 0
	v_pk_mul_f32 v[24:25], v[28:29], v[24:25]
	v_pk_mul_f32 v[28:29], v[88:89], v[6:7] op_sel_hi:[1,0]
	v_cvt_pk_bf16_f32 v24, v24, v25
	v_pk_mul_f32 v[26:27], v[26:27], v[28:29]
	v_lshlrev_b32_e32 v7, 16, v32
	v_pk_mul_f32 v[26:27], v[30:31], v[26:27]
	v_and_b32_e32 v30, 0xffff0000, v32
	v_cvt_pk_bf16_f32 v25, v26, v27
	flat_store_dwordx2 v[2:3], v[24:25] offset:64
	global_load_dwordx4 v[24:27], v[48:49], off offset:192
	v_mul_f32_e32 v28, 0xbfb8aa3b, v7
	v_mul_f32_e32 v29, 0xbfb8aa3b, v30
	v_exp_f32_e32 v28, v28
	v_exp_f32_e32 v29, v29
	v_lshlrev_b32_e32 v36, 16, v33
	v_and_b32_e32 v33, 0xffff0000, v33
	v_pk_add_f32 v[28:29], v[28:29], 1.0 op_sel_hi:[1,0]
	s_nop 0
	v_div_scale_f32 v31, s[0:1], v29, v29, v30
	v_rcp_f32_e32 v32, v31
	s_nop 0
	v_fma_f32 v37, -v31, v32, 1.0
	v_fmac_f32_e32 v32, v37, v32
	v_div_scale_f32 v37, vcc, v30, v29, v30
	v_mul_f32_e32 v38, v37, v32
	v_fma_f32 v39, -v31, v38, v37
	v_fmac_f32_e32 v38, v39, v32
	v_fma_f32 v31, -v31, v38, v37
	v_div_scale_f32 v37, s[0:1], v28, v28, v7
	v_rcp_f32_e32 v39, v37
	v_div_fmas_f32 v31, v31, v32, v38
	v_div_fixup_f32 v29, v31, v29, v30
	v_mul_f32_e32 v31, 0xbfb8aa3b, v33
	v_fma_f32 v30, -v37, v39, 1.0
	v_fmac_f32_e32 v39, v30, v39
	v_mul_f32_e32 v30, 0xbfb8aa3b, v36
	v_exp_f32_e32 v30, v30
	v_exp_f32_e32 v31, v31
	v_div_scale_f32 v32, vcc, v7, v28, v7
	v_mul_f32_e32 v38, v32, v39
	v_fma_f32 v40, -v37, v38, v32
	v_fmac_f32_e32 v38, v40, v39
	v_pk_add_f32 v[30:31], v[30:31], 1.0 op_sel_hi:[1,0]
	v_fma_f32 v32, -v37, v38, v32
	v_div_scale_f32 v37, s[0:1], v31, v31, v33
	v_rcp_f32_e32 v40, v37
	v_div_fmas_f32 v32, v32, v39, v38
	v_div_fixup_f32 v28, v32, v28, v7
	v_fma_f32 v7, -v37, v40, 1.0
	v_fmac_f32_e32 v40, v7, v40
	v_div_scale_f32 v7, vcc, v33, v31, v33
	v_mul_f32_e32 v32, v7, v40
	v_fma_f32 v38, -v37, v32, v7
	v_fmac_f32_e32 v32, v38, v40
	v_fma_f32 v7, -v37, v32, v7
	v_div_scale_f32 v37, s[0:1], v30, v30, v36
	v_rcp_f32_e32 v38, v37
	v_div_fmas_f32 v7, v7, v40, v32
	v_div_fixup_f32 v31, v7, v31, v33
	v_fma_f32 v7, -v37, v38, 1.0
	v_fmac_f32_e32 v38, v7, v38
	v_div_scale_f32 v7, vcc, v36, v30, v36
	v_mul_f32_e32 v32, v7, v38
	v_fma_f32 v33, -v37, v32, v7
	v_fmac_f32_e32 v32, v33, v38
	v_fma_f32 v7, -v37, v32, v7
	v_div_fmas_f32 v7, v7, v38, v32
	v_pk_mul_f32 v[22:23], v[22:23], v[6:7] op_sel_hi:[1,0]
	v_pk_mul_f32 v[20:21], v[20:21], v[6:7] op_sel_hi:[1,0]
	v_div_fixup_f32 v30, v7, v30, v36
	v_lshlrev_b32_e32 v7, 16, v34
	v_and_b32_e32 v32, 0xffff0000, v35
	s_waitcnt vmcnt(0)
	v_pk_mul_f32 v[22:23], v[24:25], v[22:23]
	v_pk_mul_f32 v[20:21], v[26:27], v[20:21]
	v_pk_mul_f32 v[22:23], v[28:29], v[22:23]
	v_pk_mul_f32 v[20:21], v[30:31], v[20:21]
	v_cvt_pk_bf16_f32 v22, v22, v23
	v_cvt_pk_bf16_f32 v23, v20, v21
	flat_store_dwordx2 v[2:3], v[22:23] offset:96
	global_load_dwordx4 v[20:23], v[48:49], off offset:256
	v_and_b32_e32 v28, 0xffff0000, v34
	v_mul_f32_e32 v24, 0xbfb8aa3b, v7
	v_mul_f32_e32 v25, 0xbfb8aa3b, v28
	v_exp_f32_e32 v24, v24
	v_exp_f32_e32 v25, v25
	flat_load_dwordx2 v[26:27], v[50:51] offset:160
	v_lshlrev_b32_e32 v31, 16, v35
	v_pk_add_f32 v[24:25], v[24:25], 1.0 op_sel_hi:[1,0]
	s_nop 0
	v_div_scale_f32 v29, s[0:1], v25, v25, v28
	v_rcp_f32_e32 v30, v29
	s_nop 0
	v_fma_f32 v33, -v29, v30, 1.0
	v_fmac_f32_e32 v30, v33, v30
	v_div_scale_f32 v33, vcc, v28, v25, v28
	v_mul_f32_e32 v34, v33, v30
	v_fma_f32 v35, -v29, v34, v33
	v_fmac_f32_e32 v34, v35, v30
	v_fma_f32 v29, -v29, v34, v33
	v_div_scale_f32 v33, s[0:1], v24, v24, v7
	v_rcp_f32_e32 v35, v33
	v_div_fmas_f32 v29, v29, v30, v34
	v_div_fixup_f32 v25, v29, v25, v28
	v_mul_f32_e32 v29, 0xbfb8aa3b, v32
	v_fma_f32 v28, -v33, v35, 1.0
	v_fmac_f32_e32 v35, v28, v35
	v_mul_f32_e32 v28, 0xbfb8aa3b, v31
	v_exp_f32_e32 v28, v28
	v_exp_f32_e32 v29, v29
	v_div_scale_f32 v30, vcc, v7, v24, v7
	v_mul_f32_e32 v34, v30, v35
	v_fma_f32 v36, -v33, v34, v30
	v_fmac_f32_e32 v34, v36, v35
	v_pk_add_f32 v[28:29], v[28:29], 1.0 op_sel_hi:[1,0]
	v_fma_f32 v30, -v33, v34, v30
	v_div_scale_f32 v33, s[0:1], v29, v29, v32
	v_rcp_f32_e32 v36, v33
	v_div_fmas_f32 v30, v30, v35, v34
	v_div_fixup_f32 v24, v30, v24, v7
	v_fma_f32 v7, -v33, v36, 1.0
	v_fmac_f32_e32 v36, v7, v36
	v_div_scale_f32 v7, vcc, v32, v29, v32
	v_mul_f32_e32 v30, v7, v36
	v_fma_f32 v34, -v33, v30, v7
	v_fmac_f32_e32 v30, v34, v36
	v_fma_f32 v7, -v33, v30, v7
	v_div_scale_f32 v33, s[0:1], v28, v28, v31
	v_rcp_f32_e32 v34, v33
	v_div_fmas_f32 v7, v7, v36, v30
	v_div_fixup_f32 v29, v7, v29, v32
	v_fma_f32 v7, -v33, v34, 1.0
	v_fmac_f32_e32 v34, v7, v34
	v_div_scale_f32 v7, vcc, v31, v28, v31
	v_mul_f32_e32 v30, v7, v34
	v_fma_f32 v32, -v33, v30, v7
	v_fmac_f32_e32 v30, v32, v34
	v_fma_f32 v7, -v33, v30, v7
	v_div_fmas_f32 v7, v7, v34, v30
	v_pk_mul_f32 v[18:19], v[18:19], v[6:7] op_sel_hi:[1,0]
	v_pk_mul_f32 v[16:17], v[16:17], v[6:7] op_sel_hi:[1,0]
	v_div_fixup_f32 v28, v7, v28, v31
	s_waitcnt vmcnt(0)
	v_pk_mul_f32 v[18:19], v[20:21], v[18:19]
	v_pk_mul_f32 v[16:17], v[22:23], v[16:17]
	v_pk_mul_f32 v[18:19], v[24:25], v[18:19]
	v_pk_mul_f32 v[16:17], v[28:29], v[16:17]
	v_cvt_pk_bf16_f32 v18, v18, v19
	v_cvt_pk_bf16_f32 v19, v16, v17
	flat_store_dwordx2 v[2:3], v[18:19] offset:128
	global_load_dwordx4 v[16:19], v[48:49], off offset:320
	s_nop 0
	flat_load_dwordx2 v[20:21], v[50:51] offset:192
	s_waitcnt lgkmcnt(0)
	v_lshlrev_b32_e32 v7, 16, v26
	v_and_b32_e32 v24, 0xffff0000, v26
	v_mul_f32_e32 v22, 0xbfb8aa3b, v7
	v_mul_f32_e32 v23, 0xbfb8aa3b, v24
	v_exp_f32_e32 v22, v22
	v_exp_f32_e32 v23, v23
	v_lshlrev_b32_e32 v28, 16, v27
	v_and_b32_e32 v27, 0xffff0000, v27
	v_pk_add_f32 v[22:23], v[22:23], 1.0 op_sel_hi:[1,0]
	s_nop 0
	v_div_scale_f32 v25, s[0:1], v23, v23, v24
	v_rcp_f32_e32 v26, v25
	s_nop 0
	v_fma_f32 v29, -v25, v26, 1.0
	v_fmac_f32_e32 v26, v29, v26
	v_div_scale_f32 v29, vcc, v24, v23, v24
	v_mul_f32_e32 v30, v29, v26
	v_fma_f32 v31, -v25, v30, v29
	v_fmac_f32_e32 v30, v31, v26
	v_fma_f32 v25, -v25, v30, v29
	v_div_scale_f32 v29, s[0:1], v22, v22, v7
	v_rcp_f32_e32 v31, v29
	v_div_fmas_f32 v25, v25, v26, v30
	v_div_fixup_f32 v23, v25, v23, v24
	v_mul_f32_e32 v25, 0xbfb8aa3b, v27
	v_fma_f32 v24, -v29, v31, 1.0
	v_fmac_f32_e32 v31, v24, v31
	v_mul_f32_e32 v24, 0xbfb8aa3b, v28
	v_exp_f32_e32 v24, v24
	v_exp_f32_e32 v25, v25
	v_div_scale_f32 v26, vcc, v7, v22, v7
	v_mul_f32_e32 v30, v26, v31
	v_fma_f32 v32, -v29, v30, v26
	v_fmac_f32_e32 v30, v32, v31
	v_pk_add_f32 v[24:25], v[24:25], 1.0 op_sel_hi:[1,0]
	v_fma_f32 v26, -v29, v30, v26
	v_div_scale_f32 v29, s[0:1], v25, v25, v27
	v_rcp_f32_e32 v32, v29
	v_div_fmas_f32 v26, v26, v31, v30
	v_div_fixup_f32 v22, v26, v22, v7
	v_fma_f32 v7, -v29, v32, 1.0
	v_fmac_f32_e32 v32, v7, v32
	v_div_scale_f32 v7, vcc, v27, v25, v27
	v_mul_f32_e32 v26, v7, v32
	v_fma_f32 v30, -v29, v26, v7
	v_fmac_f32_e32 v26, v30, v32
	v_fma_f32 v7, -v29, v26, v7
	v_div_scale_f32 v29, s[0:1], v24, v24, v28
	v_rcp_f32_e32 v30, v29
	v_div_fmas_f32 v7, v7, v32, v26
	v_div_fixup_f32 v25, v7, v25, v27
	v_fma_f32 v7, -v29, v30, 1.0
	v_fmac_f32_e32 v30, v7, v30
	v_div_scale_f32 v7, vcc, v28, v24, v28
	v_mul_f32_e32 v26, v7, v30
	v_fma_f32 v27, -v29, v26, v7
	v_fmac_f32_e32 v26, v27, v30
	v_fma_f32 v7, -v29, v26, v7
	v_div_fmas_f32 v7, v7, v30, v26
	v_pk_mul_f32 v[14:15], v[14:15], v[6:7] op_sel_hi:[1,0]
	v_pk_mul_f32 v[12:13], v[12:13], v[6:7] op_sel_hi:[1,0]
	v_div_fixup_f32 v24, v7, v24, v28
	s_waitcnt vmcnt(0)
	v_pk_mul_f32 v[14:15], v[16:17], v[14:15]
	v_pk_mul_f32 v[12:13], v[18:19], v[12:13]
	v_pk_mul_f32 v[14:15], v[22:23], v[14:15]
	v_pk_mul_f32 v[12:13], v[24:25], v[12:13]
	v_cvt_pk_bf16_f32 v14, v14, v15
	v_cvt_pk_bf16_f32 v15, v12, v13
	flat_store_dwordx2 v[2:3], v[14:15] offset:160
	global_load_dwordx4 v[12:15], v[48:49], off offset:384
	v_lshlrev_b32_e32 v7, 16, v20
	v_and_b32_e32 v18, 0xffff0000, v20
	v_mul_f32_e32 v16, 0xbfb8aa3b, v7
	v_mul_f32_e32 v17, 0xbfb8aa3b, v18
	v_exp_f32_e32 v16, v16
	v_exp_f32_e32 v17, v17
	v_pk_mul_f32 v[10:11], v[10:11], v[6:7] op_sel_hi:[1,0]
	v_pk_add_f32 v[16:17], v[16:17], 1.0 op_sel_hi:[1,0]
	s_nop 0
	v_div_scale_f32 v19, s[0:1], v17, v17, v18
	v_rcp_f32_e32 v20, v19
	s_waitcnt vmcnt(0)
	v_pk_mul_f32 v[10:11], v[10:11], v[12:13]
	v_fma_f32 v12, -v19, v20, 1.0
	v_fmac_f32_e32 v20, v12, v20
	v_div_scale_f32 v12, vcc, v18, v17, v18
	v_mul_f32_e32 v13, v12, v20
	v_fma_f32 v22, -v19, v13, v12
	v_fmac_f32_e32 v13, v22, v20
	v_fma_f32 v12, -v19, v13, v12
	v_div_scale_f32 v19, s[0:1], v16, v16, v7
	v_rcp_f32_e32 v22, v19
	v_div_fmas_f32 v12, v12, v20, v13
	v_div_fixup_f32 v13, v12, v17, v18
	v_lshlrev_b32_e32 v20, 16, v21
	v_fma_f32 v12, -v19, v22, 1.0
	v_fmac_f32_e32 v22, v12, v22
	v_div_scale_f32 v12, vcc, v7, v16, v7
	v_mul_f32_e32 v17, v12, v22
	v_fma_f32 v18, -v19, v17, v12
	v_fmac_f32_e32 v17, v18, v22
	v_and_b32_e32 v21, 0xffff0000, v21
	v_fma_f32 v12, -v19, v17, v12
	v_mul_f32_e32 v18, 0xbfb8aa3b, v20
	v_mul_f32_e32 v19, 0xbfb8aa3b, v21
	v_exp_f32_e32 v18, v18
	v_exp_f32_e32 v19, v19
	v_div_fmas_f32 v12, v12, v22, v17
	v_div_fixup_f32 v12, v12, v16, v7
	v_pk_mul_f32 v[10:11], v[10:11], v[12:13]
	v_pk_add_f32 v[16:17], v[18:19], 1.0 op_sel_hi:[1,0]
	v_cvt_pk_bf16_f32 v10, v10, v11
	v_div_scale_f32 v7, s[0:1], v17, v17, v21
	v_rcp_f32_e32 v18, v7
	v_pk_mul_f32 v[8:9], v[8:9], v[6:7] op_sel_hi:[1,0]
	v_fma_f32 v12, -v7, v18, 1.0
	v_fmac_f32_e32 v18, v12, v18
	v_div_scale_f32 v12, vcc, v21, v17, v21
	v_mul_f32_e32 v13, v12, v18
	v_pk_mul_f32 v[8:9], v[8:9], v[14:15]
	v_fma_f32 v14, -v7, v13, v12
	v_fmac_f32_e32 v13, v14, v18
	v_fma_f32 v7, -v7, v13, v12
	v_div_scale_f32 v12, s[0:1], v16, v16, v20
	v_rcp_f32_e32 v14, v12
	v_div_fmas_f32 v7, v7, v18, v13
	v_div_fixup_f32 v13, v7, v17, v21
	v_and_b32_e32 v18, 0xffff0000, v71
	v_fma_f32 v7, -v12, v14, 1.0
	v_fmac_f32_e32 v14, v7, v14
	v_div_scale_f32 v7, vcc, v20, v16, v20
	v_mul_f32_e32 v15, v7, v14
	v_fma_f32 v17, -v12, v15, v7
	v_fmac_f32_e32 v15, v17, v14
	v_fma_f32 v7, -v12, v15, v7
	v_div_fmas_f32 v7, v7, v14, v15
	v_div_fixup_f32 v12, v7, v16, v20
	v_pk_mul_f32 v[8:9], v[8:9], v[12:13]
	v_lshlrev_b32_e32 v7, 16, v70
	v_cvt_pk_bf16_f32 v11, v8, v9
	flat_store_dwordx2 v[2:3], v[10:11] offset:192
	global_load_dwordx4 v[8:11], v[48:49], off offset:448
	v_and_b32_e32 v14, 0xffff0000, v70
	v_mul_f32_e32 v12, 0xbfb8aa3b, v7
	v_mul_f32_e32 v13, 0xbfb8aa3b, v14
	v_exp_f32_e32 v12, v12
	v_exp_f32_e32 v13, v13
	v_pk_mul_f32 v[4:5], v[4:5], v[6:7] op_sel_hi:[1,0]
	v_pk_add_f32 v[12:13], v[12:13], 1.0 op_sel_hi:[1,0]
	s_nop 0
	v_div_scale_f32 v15, s[0:1], v13, v13, v14
	v_rcp_f32_e32 v16, v15
	s_waitcnt vmcnt(0)
	v_pk_mul_f32 v[4:5], v[4:5], v[8:9]
	v_fma_f32 v8, -v15, v16, 1.0
	v_fmac_f32_e32 v16, v8, v16
	v_div_scale_f32 v8, vcc, v14, v13, v14
	v_mul_f32_e32 v9, v8, v16
	v_fma_f32 v17, -v15, v9, v8
	v_fmac_f32_e32 v9, v17, v16
	v_fma_f32 v8, -v15, v9, v8
	v_div_scale_f32 v15, s[0:1], v12, v12, v7
	v_rcp_f32_e32 v17, v15
	v_div_fmas_f32 v8, v8, v16, v9
	v_div_fixup_f32 v9, v8, v13, v14
	v_lshlrev_b32_e32 v16, 16, v71
	v_fma_f32 v8, -v15, v17, 1.0
	v_fmac_f32_e32 v17, v8, v17
	v_div_scale_f32 v8, vcc, v7, v12, v7
	v_mul_f32_e32 v13, v8, v17
	v_fma_f32 v14, -v15, v13, v8
	v_fmac_f32_e32 v13, v14, v17
	v_fma_f32 v8, -v15, v13, v8
	v_mul_f32_e32 v14, 0xbfb8aa3b, v16
	v_mul_f32_e32 v15, 0xbfb8aa3b, v18
	v_exp_f32_e32 v14, v14
	v_exp_f32_e32 v15, v15
	v_div_fmas_f32 v8, v8, v17, v13
	v_div_fixup_f32 v8, v8, v12, v7
	v_pk_mul_f32 v[4:5], v[4:5], v[8:9]
	v_pk_add_f32 v[12:13], v[14:15], 1.0 op_sel_hi:[1,0]
	v_cvt_pk_bf16_f32 v4, v4, v5
	v_div_scale_f32 v7, s[0:1], v13, v13, v18
	v_rcp_f32_e32 v14, v7
	v_pk_mul_f32 v[0:1], v[0:1], v[6:7] op_sel_hi:[1,0]
	v_fma_f32 v6, -v7, v14, 1.0
	v_fmac_f32_e32 v14, v6, v14
	v_div_scale_f32 v6, vcc, v18, v13, v18
	v_mul_f32_e32 v8, v6, v14
	v_fma_f32 v9, -v7, v8, v6
	v_fmac_f32_e32 v8, v9, v14
	v_div_scale_f32 v9, s[0:1], v12, v12, v16
	v_pk_mul_f32 v[0:1], v[0:1], v[10:11]
	v_rcp_f32_e32 v10, v9
	v_fma_f32 v6, -v7, v8, v6
	v_div_fmas_f32 v6, v6, v14, v8
	v_div_fixup_f32 v7, v6, v13, v18
	v_fma_f32 v6, -v9, v10, 1.0
	v_fmac_f32_e32 v10, v6, v10
	v_div_scale_f32 v6, vcc, v16, v12, v16
	v_mul_f32_e32 v8, v6, v10
	v_fma_f32 v11, -v9, v8, v6
	v_fmac_f32_e32 v8, v11, v10
	v_fma_f32 v6, -v9, v8, v6
	v_div_fmas_f32 v6, v6, v10, v8
	v_div_fixup_f32 v6, v6, v12, v16
	v_pk_mul_f32 v[0:1], v[0:1], v[6:7]
	s_nop 0
	v_cvt_pk_bf16_f32 v5, v0, v1
	flat_store_dwordx2 v[2:3], v[4:5] offset:224
	s_waitcnt lgkmcnt(0)
	s_barrier
	s_cbranch_scc1 .LBB0_495
